# static s_setprio 1 for waves 0-3 (lower half) in the scan loop and the attention phase
# baseline (speedup 1.0000x reference)
.LBB0_349:
	s_or_b64 exec, exec, s[0:1]
	s_ashr_i32 s0, s2, 4
	s_ashr_i32 s1, s0, 31
	s_waitcnt vmcnt(0)
	v_lshrrev_b32_e32 v13, 3, v143
	s_lshl_b64 s[0:1], s[0:1], 23
	s_ashr_i32 s3, s2, 31
	v_lshl_or_b32 v130, v13, 12, s0
	v_mov_b32_e32 v131, s1
	v_lshl_add_u64 v[2:3], s[4:5], 0, v[130:131]
	s_mov_b32 s1, 0
	s_lshl_b32 s0, s30, 1
	s_lshl_b64 s[10:11], s[2:3], 19
	v_lshl_add_u64 v[2:3], v[2:3], 0, s[0:1]
	s_add_u32 s0, s97, s10
	s_addc_u32 s1, s33, s11
	v_mov_b32_e32 v11, 0
	s_add_u32 s4, s70, s10
	v_lshlrev_b32_e32 v134, 4, v143
	s_addc_u32 s5, s71, s11
	v_mov_b32_e32 v135, v11
	v_lshl_add_u64 v[4:5], s[4:5], 0, v[134:135]
	s_mov_b32 s4, 0xe000000
	v_and_b32_e32 v38, 7, v143
	v_add_co_u32_e32 v6, vcc, s4, v4
	v_lshlrev_b32_e32 v10, 5, v38
	s_nop 0
	v_addc_co_u32_e32 v7, vcc, 0, v5, vcc
	s_brev_b32 s4, 8
	v_lshl_add_u64 v[2:3], v[2:3], 0, v[10:11]
	v_add_co_u32_e32 v8, vcc, s4, v4
	global_load_dwordx4 v[14:17], v[2:3], off offset:16
	global_load_dwordx4 v[26:29], v[2:3], off
	v_lshl_add_u64 v[2:3], s[0:1], 0, v[134:135]
	v_addc_co_u32_e32 v9, vcc, 0, v5, vcc
	s_movk_i32 s4, 0x2000
	v_add_co_u32_e32 v2, vcc, s4, v2
	s_mov_b32 s4, 0xe002000
	s_nop 0
	v_addc_co_u32_e32 v3, vcc, 0, v3, vcc
	global_load_dwordx4 v[18:21], v[6:7], off
	global_load_dwordx4 v[22:25], v[8:9], off
	v_add_co_u32_e32 v6, vcc, s4, v4
	s_mov_b32 s4, 0x10002000
	s_nop 0
	v_addc_co_u32_e32 v7, vcc, 0, v5, vcc
	s_lshl_b64 s[22:23], s[2:3], 15
	global_load_dwordx4 v[30:33], v[2:3], off
	global_load_dwordx4 v[66:69], v[6:7], off
	v_add_co_u32_e32 v2, vcc, s4, v4
	s_add_u32 s4, s70, s22
	s_nop 0
	v_addc_co_u32_e32 v3, vcc, 0, v5, vcc
	s_addc_u32 s5, s71, s23
	v_lshlrev_b32_e32 v4, 4, v142
	v_mov_b32_e32 v5, v11
	v_lshl_add_u64 v[6:7], s[4:5], 0, v[4:5]
	s_mov_b32 s4, 0x17200000
	s_lshl_b64 s[24:25], s[2:3], 17
	v_add_co_u32_e32 v6, vcc, s4, v6
	s_add_u32 s4, s50, s24
	s_nop 0
	v_addc_co_u32_e32 v7, vcc, 0, v7, vcc
	global_load_dwordx4 v[78:81], v[2:3], off
	global_load_dwordx4 v[74:77], v[6:7], off
	s_addc_u32 s5, s51, s25
	v_and_b32_e32 v2, 0xff0, v134
	global_load_dwordx4 v[34:37], v134, s[0:1]
	global_load_dwordx4 v[70:73], v2, s[4:5]
	v_and_b32_e32 v1, 0xf0, v134
	s_lshr_b32 s12, s12, 2
	v_and_b32_e32 v12, 15, v143
	v_add_u32_e32 v5, 0, v1
	v_and_b32_e32 v1, 0x70, v134
	s_and_b32 s12, s12, 0x3ffffff0
	v_add_u32_e32 v6, 0, v1
	v_or_b32_e32 v1, s12, v12
	s_movk_i32 s13, 0x90
	v_lshrrev_b32_e32 v133, 4, v142
	v_mul_lo_u32 v3, v1, s13
	v_add_u32_e32 v161, 0, v3
	v_lshlrev_b32_e32 v3, 2, v133
	v_or_b32_e32 v7, s12, v3
	s_add_i32 s12, 0, 0x11c00
	s_movk_i32 s13, 0x210
	v_mov_b32_e32 v8, s12
	v_or_b32_e32 v42, 32, v12
	v_mad_u32_u24 v9, v13, s13, v8
	v_add_u32_e32 v39, 0x200, v143
	v_mul_u32_u24_e32 v41, 0x110, v12
	v_mul_u32_u24_e32 v167, 0x90, v12
	v_or_b32_e32 v153, 16, v3
	v_or_b32_e32 v152, 32, v3
	v_or_b32_e32 v151, 48, v3
	v_or_b32_e32 v150, 64, v3
	v_or_b32_e32 v149, 0x50, v3
	v_or_b32_e32 v148, 0x60, v3
	v_or_b32_e32 v135, 0x70, v3
	v_mad_u32_u24 v12, v12, s13, v8
	v_mad_u32_u24 v8, v42, s13, v8
	v_or_b32_e32 v2, s24, v2
	v_mov_b32_e32 v3, s25
	s_mov_b64 s[12:13], 0x16a01000
	v_lshlrev_b32_e32 v132, 4, v38
	v_lshlrev_b32_e32 v163, 3, v133
	v_lshlrev_b32_e32 v165, 6, v38
	v_lshrrev_b32_e32 v38, 4, v143
	v_lshrrev_b32_e32 v40, 4, v39
	v_lshrrev_b32_e32 v39, 3, v39
	v_lshlrev_b32_e32 v175, 1, v152
	v_lshl_add_u64 v[136:137], v[2:3], 0, s[12:13]
	v_or_b32_e32 v2, s22, v4
	v_mov_b32_e32 v3, s23
	s_mov_b64 s[12:13], 0x17200400
	v_or_b32_e32 v140, s10, v134
	s_and_b32 s10, s2, 15
	s_movk_i32 s0, 0x100
	v_add_u32_e32 v164, 0, v163
	v_lshlrev_b32_e32 v7, 2, v7
	v_mul_u32_u24_e32 v38, 0x110, v38
	v_mul_u32_u24_e32 v13, 0x90, v13
	v_mul_u32_u24_e32 v40, 0x110, v40
	v_mul_u32_u24_e32 v39, 0x90, v39
	v_mul_u32_u24_e32 v43, 0x110, v42
	v_add_u32_e32 v44, 0, v175
	v_lshl_add_u64 v[138:139], v[2:3], 0, s[12:13]
	s_lshl_b32 s10, s10, 8
	v_mbcnt_lo_u32_b32 v2, -1, 0
	v_cmp_gt_u32_e64 s[4:5], 64, v143
	v_cmp_gt_u32_e64 s[0:1], s0, v143
	v_lshlrev_b32_e32 v162, 3, v142
	v_and_b32_e32 v166, 48, v143
	v_lshlrev_b32_e32 v168, 2, v153
	v_lshlrev_b32_e32 v169, 2, v152
	v_lshlrev_b32_e32 v170, 2, v151
	v_lshlrev_b32_e32 v171, 2, v150
	v_lshlrev_b32_e32 v172, 2, v149
	v_lshlrev_b32_e32 v173, 2, v148
	v_lshlrev_b32_e32 v174, 2, v135
	v_mov_b32_e32 v141, s11
	v_or3_b32 v144, v130, s10, v10
	v_mov_b32_e32 v145, v131
	s_mov_b32 s31, 31
	s_mov_b64 s[10:11], 0x1ae40000
	s_add_i32 s34, 0, 0x11a00
	v_mbcnt_hi_u32_b32 v177, -1, v2
	v_mov_b32_e32 v178, 0x358637bd
	s_mov_b32 s35, 0x800000
	s_mov_b32 s36, 0x12600000
	s_mov_b64 s[12:13], 0x1000
	s_mov_b64 s[22:23], 0x400
	s_mov_b64 s[24:25], 0x4000
	s_mov_b64 s[26:27], 0x40000
	v_add_u32_e32 v182, v5, v38
	v_add_u32_e32 v180, v6, v13
	v_add_u32_e32 v181, v5, v40
	v_add_u32_e32 v179, v6, v39
	v_add_u32_e32 v157, v164, v41
	v_add_u32_e32 v159, v12, v7
	v_add_u32_e32 v158, v164, v43
	v_add_u32_e32 v156, v44, v167
	v_add_u32_e32 v155, v8, v7
	v_add_u32_e32 v154, v9, v165
	v_mov_b32_e32 v10, v11
	v_mov_b32_e32 v12, v11
	v_mov_b32_e32 v13, v11
	v_mov_b32_e32 v38, v11
	v_mov_b32_e32 v39, v11
	v_mov_b32_e32 v40, v11
	v_mov_b32_e32 v41, v11
	v_mov_b32_e32 v42, v11
	v_mov_b32_e32 v43, v11
	v_mov_b32_e32 v44, v11
	v_mov_b32_e32 v45, v11
	v_mov_b32_e32 v46, v11
	v_mov_b32_e32 v47, v11
	v_mov_b32_e32 v48, v11
	v_mov_b32_e32 v49, v11
	v_mov_b32_e32 v50, v11
	v_mov_b32_e32 v51, v11
	v_mov_b32_e32 v52, v11
	v_mov_b32_e32 v53, v11
	v_mov_b32_e32 v54, v11
	v_mov_b32_e32 v55, v11
	v_mov_b32_e32 v56, v11
	v_mov_b32_e32 v57, v11
	v_mov_b32_e32 v62, v11
	v_mov_b32_e32 v63, v11
	v_mov_b32_e32 v64, v11
	v_mov_b32_e32 v65, v11
	v_mov_b32_e32 v58, v11
	v_mov_b32_e32 v59, v11
	v_mov_b32_e32 v60, v11
	v_mov_b32_e32 v61, v11
	v_readfirstlane_b32 s98, v143
	s_lshr_b32 s98, s98, 8
	s_cmp_lg_u32 s98, 0
	s_cbranch_scc1 .Lprio_scan_done
	s_setprio 1

.LBB0_1110:
	s_cmp_lt_i32 s72, 11
	s_cselect_b64 s[4:5], -1, 0
	s_and_b64 s[56:57], s[4:5], s[0:1]
	s_xor_b64 s[0:1], s[56:57], -1
	s_cmpk_gt_i32 s2, 0x2ff
	s_cselect_b64 s[4:5], -1, 0
	s_or_b64 s[0:1], s[0:1], s[4:5]
	s_and_b64 vcc, exec, s[0:1]
	s_cbranch_vccnz .LBB0_1179
	s_waitcnt vmcnt(0)
	v_lshrrev_b32_e32 v4, 8, v143
	v_lshlrev_b32_e32 v22, 3, v4
	v_mul_u32_u24_e32 v31, 0x1080, v4
	v_add_u32_e32 v4, 0x200, v143
	v_lshrrev_b32_e32 v33, 3, v4
	v_lshrrev_b32_e32 v4, 8, v4
	v_bfe_u32 v2, v143, 4, 2
	v_lshlrev_b32_e32 v24, 3, v4
	v_mul_u32_u24_e32 v43, 0x1080, v4
	v_or_b32_e32 v4, 0x400, v143
	s_movk_i32 s14, 0x420
	s_movk_i32 s16, 0x500
	v_lshrrev_b32_e32 v44, 3, v4
	v_cmp_gt_u32_e64 s[14:15], s14, v4
	v_cmp_gt_u32_e64 s[16:17], s16, v4
	v_lshrrev_b32_e32 v4, 8, v4
	v_lshlrev_b32_e32 v32, 2, v2
	v_and_b32_e32 v1, 15, v143
	v_lshlrev_b32_e32 v26, 3, v4
	v_mul_u32_u24_e32 v46, 0x1080, v4
	v_add_u32_e32 v4, 0x600, v143
	v_or_b32_e32 v7, 2, v32
	v_min_u32_e32 v3, 3, v1
	v_lshlrev_b32_e32 v18, 3, v2
	v_lshrrev_b32_e32 v5, 8, v4
	v_lshl_add_u32 v30, v2, 4, 0
	v_cmp_gt_u32_e64 s[24:25], v7, v1
	v_or_b32_e32 v7, 3, v32
	v_or_b32_e32 v21, 0x2000, v3
	v_and_b32_e32 v3, 7, v143
	v_and_b32_e32 v23, 0xff, v143
	s_movk_i32 s3, 0x7f
	v_lshrrev_b32_e32 v29, 3, v143
	v_lshlrev_b32_e32 v28, 3, v5
	v_mul_u32_u24_e32 v47, 0x1080, v5
	v_sub_u32_e32 v2, v30, v18
	v_lshrrev_b32_e32 v48, 3, v4
	v_or_b32_e32 v5, 0x80, v1
	v_cmp_gt_u32_e64 s[26:27], v7, v1
	v_or_b32_e32 v7, 0x82, v32
	s_movk_i32 s34, 0x210
	v_mov_b32_e32 v19, 0
	s_movk_i32 s0, 0xa0
	v_lshlrev_b32_e32 v20, 3, v3
	v_lshl_add_u32 v25, v3, 4, 0
	v_cmp_lt_u32_e64 s[4:5], s3, v23
	s_movk_i32 s3, 0x84
	v_mul_u32_u24_e32 v3, 0x90, v29
	s_movk_i32 s8, 0x1ff
	s_movk_i32 s10, 0x220
	s_movk_i32 s12, 0x300
	v_mul_u32_u24_e32 v4, 0x90, v48
	v_mul_u32_u24_e32 v6, 0x90, v1
	v_cmp_gt_u32_e64 s[28:29], v7, v5
	v_or_b32_e32 v7, 0x83, v32
	v_mad_u32_u24 v49, v1, s34, v2
	v_mbcnt_lo_u32_b32 v2, -1, 0
	v_cmp_gt_u32_e64 s[0:1], s0, v23
	s_mov_b32 s63, 0
	v_cmp_gt_u32_e64 s[6:7], s3, v23
	v_lshl_add_u32 v27, v23, 1, 0
	s_movk_i32 s3, 0x90
	v_cmp_lt_u32_e64 s[8:9], s8, v143
	v_cmp_gt_u32_e64 s[10:11], s10, v143
	v_cmp_gt_u32_e64 s[12:13], s12, v143
	v_mul_u32_u24_e32 v42, 0x90, v33
	v_mul_u32_u24_e32 v45, 0x90, v44
	v_cmp_gt_u32_e64 s[18:19], 4, v1
	v_cmp_gt_u32_e64 s[20:21], v32, v1
	v_cmp_lt_u32_e64 s[22:23], v32, v1
	v_cmp_gt_u32_e64 s[30:31], v7, v5
	v_lshl_add_u64 v[34:35], s[44:45], 0, v[18:19]
	s_lshl_b32 s42, s2, 5
	s_lshl_b32 s43, s74, 5
	v_add_u32_e32 v50, v25, v3
	v_add_u32_e32 v51, v30, v6
	s_mov_b32 s58, 0xff800000
	v_add_u32_e32 v52, v25, v4
	v_lshlrev_b32_e32 v18, 1, v18
	v_lshlrev_b32_e32 v36, 2, v20
	v_mbcnt_hi_u32_b32 v53, -1, v2
	v_mov_b32_e32 v54, 0xff800000
	s_mov_b32 s59, s2
	s_mov_b32 s60, s2
	v_readfirstlane_b32 s98, v143
	s_lshr_b32 s98, s98, 8
	s_cmp_lg_u32 s98, 0
	s_cbranch_scc1 .Lprio_att_done
	s_setprio 1
